# last 486 gate ops computed in the idle tail of the gemm_in phase (stash in the unused workspace slab); gate pass 16 rounds instead of 17
# speedup vs baseline: 1.0048x; 1.0048x over previous
; template <bool WIDE = false>
; DI void gemm_core(f32x4 (&acc)[4][4], const GOp& g, LAS char* lds, const int tidx, const bool have_first, const bool has_next, const GOp& gn, const bool fw16 = false) {
;     const int tid = tidx, lane = tid & 63, w = tid >> 6, wm = w >> 1, wn = w & 1;
;     unsigned oa[4], ob[4];
; #pragma unroll
;     for (int j = 0; j < 4; ++j) {
;         const int o = (j * 4 + w) * 1024 + lane * 16, row = o >> 7, cs = (o >> 4) & 7, c = cs ^ ((row >> 1) & 7);
;         oa[j] = (unsigned)(row * g.lda + c * 8); ob[j] = (unsigned)(row * g.ldb + c * 8);
;     }
;     const int nk = g.K >> 6;
;     const int fr = lane & 15, fq = lane >> 4;
;     const int sw = (fq ^ (fr >> 1)) << 4;
;     const int aoff = (wm * 64 + fr) * 128, boff = 16384 + (wn * 64 + fr) * 128;
; DI void phase_merge(const Params& p, int l, LAS char* lds) {
;     ...
;     auto op_of = [&](int f) {
;         if (f < 4 * ntl) {
;             const int br = f / ntl, i = vb + (f - br * ntl) * G, mt = i >> 3, nt = i & 7;
;             return GOp{h + (size_t)mt * 128 * 1024, W + W_IN + (size_t)(3328 + br * 1024 + nt * 128) * 1024, 1024, 1024, 1024, 2 * (mt + nt)};
;         }
;         const int f2 = f - 4 * ntl, k = f2 >> 2, br = f2 & 3, i = vb + k * G, mt = i >> 3, nt = i & 7;
;         const int koff = (br == 0) ? 0 : (br == 1) ? 256 : (br == 2) ? 768 : 1024;
;         const int kk = (br == 1) ? 512 : 256;
;         const size_t woff = (br == 0) ? W_OP : (br == 1) ? W_OM : (br == 2) ? W_OC : W_OS;
;         return GOp{u + (size_t)mt * 128 * 1280 + koff, W + woff + (size_t)nt * 128 * kk, 1280, kk, kk, mt + nt};
;     };
;     f32x4 acc[4][4];
;     bool inflight = false;
;     unsigned sq[4][4], sqn[4][4];
; #pragma unroll
;     for (int mi = 0; mi < 4; ++mi)
; #pragma unroll
;         for (int ni = 0; ni < 4; ++ni) { sq[mi][ni] = 0x01010101u; sqn[mi][ni] = 0x01010101u; }
;     for (int f = 0; f < nops; ++f) {
;         const bool gate = f < 4 * ntl;
;         int br, i;
;         if (gate) { br = f / ntl; i = vb + (f - br * ntl) * G; } else { const int f2 = f - 4 * ntl; br = f2 & 3; i = vb + (f2 >> 2) * G; }
;         const int mt = i >> 3, nt = i & 7;
;         const bool has_next = f + 1 < nops;
;         const GOp g = op_of(f), gn = op_of(has_next ? f + 1 : f);
;         unsigned* st = stash + (size_t)(i * 4 + br) * 4096;
.Lgp_entry:
	s_waitcnt vmcnt(0)
	v_mov_b32_e32 v2, v151
	v_lshlrev_b32_e32 v4, 4, v2
	v_and_b32_e32 v67, 0xfffffc00, v4
	v_lshrrev_b32_e32 v4, 4, v2
	v_xor_b32_e32 v4, v4, v2
	v_lshlrev_b32_e32 v7, 7, v2
	v_readlane_b32 s8, v228, 30
	v_and_b32_e32 v5, 48, v2
	v_and_b32_e32 v6, 0xfffffc00, v7
	v_lshlrev_b32_e32 v4, 3, v4
	v_lshlrev_b32_e32 v9, 3, v2
	s_movk_i32 s4, 0x70
	s_mul_i32 s0, s8, 0x13a0000
	v_and_b32_e32 v1, 64, v2
	v_and_b32_e32 v3, 15, v2
	v_and_or_b32 v148, v4, 56, v6
	v_bitop3_b32 v10, v9, v2, 48 bitop3:0x78
	v_bitop3_b32 v86, v9, s4, v5 bitop3:0x48
	v_ashrrev_i32_e32 v5, 1, v2
	s_movk_i32 s4, 0xffc0
	v_and_b32_e32 v66, 16, v2
	v_lshrrev_b32_e32 v2, 2, v2
	s_mul_hi_i32 s1, s8, 0x13a0000
	s_add_u32 s0, s98, s0
	v_add_u32_e32 v4, 0x8000, v148
	v_add_u32_e32 v6, 0x10000, v148
	v_add_u32_e32 v8, 0x18000, v148
	v_and_or_b32 v87, v5, s4, v3
	v_and_b32_e32 v89, 0x2780, v7
	v_mov_b32_e32 v5, v149
	v_mov_b32_e32 v7, v149
	v_mov_b32_e32 v9, v149
	v_and_b32_e32 v2, 8, v2
	s_addc_u32 s1, s99, s1
	v_lshlrev_b32_e32 v88, 7, v87
	v_bitop3_b32 v90, v10, 64, v168 bitop3:0x6c
	s_mov_b64 s[46:47], 0
	v_lshlrev_b32_e32 v68, 1, v2
	v_lshlrev_b64 v[70:71], 1, v[148:149]
	v_lshlrev_b64 v[72:73], 1, v[4:5]
	v_lshlrev_b64 v[74:75], 1, v[6:7]
	v_lshlrev_b64 v[76:77], 1, v[8:9]
	v_readlane_b32 s4, v229, 39
	v_readfirstlane_b32 s100, v67
	s_mov_b32 s56, s4
	v_lshlrev_b32_e32 v1, 2, v151
	v_and_b32_e32 v77, 64, v151
	v_lshrrev_b32_e32 v3, 2, v151
	v_and_b32_e32 v3, 12, v3
	v_or_b32_e32 v77, v77, v3
	v_lshlrev_b32_e32 v77, 2, v77
	v_readlane_b32 s60, v228, 19
	v_readlane_b32 s61, v228, 20
	v_readlane_b32 s62, v229, 53
	v_readlane_b32 s63, v229, 54
	s_lshl_b32 s5, s8, 14
	s_add_u32 s62, s62, s5
	s_addc_u32 s63, s63, 0
	s_cmpk_gt_u32 s56, 0x1e39
	s_cbranch_scc1 .Lgp_done
.Lgp_tile:
	s_mov_b32 s55, s56
	s_mov_b32 s54, 0
	s_cmp_ge_u32 s55, 0x808
	s_cselect_b32 s5, 1, 0
	s_add_u32 s54, s54, s5
	s_mul_i32 s5, s5, 0x808
	s_sub_u32 s55, s55, s5
	s_cmp_ge_u32 s55, 0x808
	s_cselect_b32 s5, 1, 0
	s_add_u32 s54, s54, s5
	s_mul_i32 s5, s5, 0x808
	s_sub_u32 s55, s55, s5
	s_cmp_ge_u32 s55, 0x808
	s_cselect_b32 s5, 1, 0
	s_add_u32 s54, s54, s5
	s_mul_i32 s5, s5, 0x808
	s_sub_u32 s55, s55, s5
	s_lshr_b32 s48, s55, 3
	s_and_b32 s5, s55, 7
	s_lshl_b32 s6, s54, 3
	s_add_u32 s50, s5, s6
	s_add_u32 s50, s50, 26
	s_add_i32 s23, s56, s22
	s_cmpk_lt_u32 s23, 0x1e3a
	s_cselect_b64 s[42:43], -1, 0
	s_cbranch_scc0 .Lgp_nonext
	s_mov_b32 s52, s23
	s_mov_b32 s57, 0
	s_cmp_ge_u32 s52, 0x808
	s_cselect_b32 s5, 1, 0
	s_add_u32 s57, s57, s5
	s_mul_i32 s5, s5, 0x808
	s_sub_u32 s52, s52, s5
	s_cmp_ge_u32 s52, 0x808
	s_cselect_b32 s5, 1, 0
	s_add_u32 s57, s57, s5
	s_mul_i32 s5, s5, 0x808
	s_sub_u32 s52, s52, s5
	s_cmp_ge_u32 s52, 0x808
	s_cselect_b32 s5, 1, 0
	s_add_u32 s57, s57, s5
	s_mul_i32 s5, s5, 0x808
	s_sub_u32 s52, s52, s5
	s_lshr_b32 s38, s52, 3
	s_and_b32 s5, s52, 7
	s_lshl_b32 s6, s57, 3
	s_add_u32 s44, s5, s6
	s_add_u32 s44, s44, 26

; DI void phase_merge(const Params& p, int l, LAS char* lds) {
;     ...
;         if (has_next && f + 1 >= 4 * ntl) {
;             const int f2 = f + 1 - 4 * ntl;
;             const unsigned* stn = stash + (size_t)((vb + (f2 >> 2) * G) * 4 + (f2 & 3)) * 4096;
; #pragma unroll
;             for (int mi = 0; mi < 4; ++mi)
; #pragma unroll
;                 for (int ni = 0; ni < 4; ++ni) sqn[mi][ni] = stn[(mi * 4 + ni) * 256];
;         }
.LBB0_253:
	s_cmp_lt_i32 s69, s66
	s_cselect_b64 s[4:5], -1, 0
	s_xor_b64 s[6:7], s[50:51], -1
	s_or_b64 s[4:5], s[4:5], s[6:7]
	s_and_b64 vcc, exec, s[4:5]
	s_cbranch_vccnz .LBB0_255
	s_sub_i32 s4, s69, s66
	s_lshr_b32 s4, s4, 2
	s_mul_i32 s4, s4, s22
	s_add_i32 s4, s4, s73
	s_and_b32 s5, s69, 3
	s_cmp_eq_u32 s5, 3
	s_cselect_b32 s6, 1, 0
	s_cmp_ge_u32 s4, 0x622
	s_cselect_b32 s7, 1, 0
	s_and_b32 s6, s6, s7
	s_cmp_eq_u32 s6, 1
	s_cbranch_scc1 .Lsq_scr
	s_lshl_b32 s4, s4, 2
	s_or_b32 s4, s4, s5
	s_ashr_i32 s5, s4, 31
	s_lshl_b64 s[4:5], s[4:5], 14
	s_branch .Lsq_adr
.Lsq_scr:
	s_sub_u32 s4, s4, 0x622
	s_lshl_b32 s4, s4, 14
	s_add_u32 s4, s4, 0x12260c00
	s_mov_b32 s5, 0
.Lsq_adr:
	v_lshl_add_u64 v[2:3], v[152:153], 0, s[4:5]
	v_add_co_u32_e32 v84, vcc, 0x1000, v2
	global_load_dword v190, v[2:3], off
	global_load_dword v189, v[2:3], off offset:1024
	global_load_dword v188, v[2:3], off offset:2048
	global_load_dword v187, v[2:3], off offset:3072
	v_addc_co_u32_e32 v85, vcc, 0, v3, vcc
	global_load_dword v194, v[84:85], off
	global_load_dword v193, v[84:85], off offset:1024
	global_load_dword v192, v[84:85], off offset:2048
	global_load_dword v191, v[84:85], off offset:3072
	v_add_co_u32_e32 v84, vcc, 0x2000, v2
	s_nop 1
	v_addc_co_u32_e32 v85, vcc, 0, v3, vcc
	v_add_co_u32_e32 v2, vcc, 0x3000, v2
	global_load_dword v198, v[84:85], off
	global_load_dword v197, v[84:85], off offset:1024
	global_load_dword v196, v[84:85], off offset:2048
	global_load_dword v195, v[84:85], off offset:3072
	v_addc_co_u32_e32 v3, vcc, 0, v3, vcc
	global_load_dword v202, v[2:3], off
	global_load_dword v201, v[2:3], off offset:1024
	global_load_dword v200, v[2:3], off offset:2048
	global_load_dword v199, v[2:3], off offset:3072

; #define LAS __attribute__((address_space(3)))
; DI void gload_lds16(const void* g, LAS char* l) { __builtin_amdgcn_global_load_lds((const unsigned*)g, (LAS unsigned*)l, 16, 0, 0); }
; template <bool WIDE = false>
; DI void gemm_core(f32x4 (&acc)[4][4], const GOp& g, LAS char* lds, const int tidx, const bool have_first, const bool has_next, const GOp& gn, const bool fw16 = false) {
;     ...
;     const int nk = g.K >> 6;
;     const int fr = lane & 15, fq = lane >> 4;
;     const int sw = (fq ^ (fr >> 1)) << 4;
;     const int aoff = (wm * 64 + fr) * 128, boff = 16384 + (wn * 64 + fr) * 128;
;     if (!have_first) gemm_issue(g, 0, lds, w, lane);
;     for (int kt = 0; kt < nk; ++kt) {
;         if (kt == 0 && have_first && fw16) {
;             asm volatile("s_waitcnt vmcnt(8) lgkmcnt(0)" ::: "memory");
;             __builtin_amdgcn_s_barrier();
;             asm volatile("" ::: "memory");
;         } else {
;             asm volatile("s_waitcnt vmcnt(0)" ::: "memory");
;             __syncthreads();
;         }
;         if (kt + 1 < nk) {
;             LAS char* base = lds + ((kt + 1) & 1) * 32768 + w * 1024;
;             const int kn = ((kt + 1 + g.krot) & (nk - 1)) * 64;
;             const bf16_t* Ak = g.A + kn; const bf16_t* Bk = g.Bt + kn;
; #pragma unroll
;             for (int j = 0; j < 4; ++j) { gload_lds16(Ak + oa[j], base + j * 4096); gload_lds16(Bk + ob[j], base + 16384 + j * 4096); }
;         } else if (has_next) gemm_issue(gn, 0, lds, w, lane);
; DI void phase_merge(const Params& p, int l, LAS char* lds) {
;     ...
;     auto op_of = [&](int f) {
;         if (f < 4 * ntl) {
;             const int br = f / ntl, i = vb + (f - br * ntl) * G, mt = i >> 3, nt = i & 7;
;             return GOp{h + (size_t)mt * 128 * 1024, W + W_IN + (size_t)(3328 + br * 1024 + nt * 128) * 1024, 1024, 1024, 1024, 2 * (mt + nt)};
.LBB0_402:
	v_readlane_b32 s33, v229, 39
	s_nop 0
	s_cmp_lt_u32 s33, 26
	s_cbranch_scc1 .Lgx_skip
	s_sub_u32 s33, s33, 26
	v_lshlrev_b32_e32 v1, 2, v151
	v_and_b32_e32 v77, 64, v151
	v_lshrrev_b32_e32 v3, 2, v151
	v_and_b32_e32 v3, 12, v3
	v_or_b32_e32 v77, v77, v3
	v_lshlrev_b32_e32 v77, 2, v77
	s_add_u32 s4, s33, 0x622
	s_lshr_b32 s48, s4, 3
	s_and_b32 s5, s4, 7
	s_add_u32 s50, s5, 50
	v_readlane_b32 s52, v229, 53
	v_readlane_b32 s53, v229, 54
	v_readlane_b32 s6, v228, 30
	s_lshl_b32 s6, s6, 14
	s_lshl_b32 s5, s5, 9
	s_add_u32 s6, s6, s5
	s_add_u32 s6, s6, 0x3000
	s_add_u32 s52, s52, s6
	s_addc_u32 s53, s53, 0
	s_lshl_b32 s4, s33, 14
	s_add_u32 s4, s4, 0x1b120c00
	s_add_u32 s40, s98, s4
	s_addc_u32 s41, s99, 0
	s_mov_b64 s[46:47], 0
	s_mov_b64 s[42:43], 0
	global_load_dword v66, v77, s[52:53] offset:0
	global_load_dword v68, v77, s[52:53] offset:4
	global_load_dword v69, v77, s[52:53] offset:8
	global_load_dword v93, v77, s[52:53] offset:12
	global_load_dword v146, v77, s[52:53] offset:64
	global_load_dword v147, v77, s[52:53] offset:68
	global_load_dword v148, v77, s[52:53] offset:72
	global_load_dword v160, v77, s[52:53] offset:76
	global_load_dword v161, v77, s[52:53] offset:128
	global_load_dword v182, v77, s[52:53] offset:132
	global_load_dword v183, v77, s[52:53] offset:136
	global_load_dword v184, v77, s[52:53] offset:140
	global_load_dword v185, v77, s[52:53] offset:192
	global_load_dword v71, v77, s[52:53] offset:196
	global_load_dword v73, v77, s[52:53] offset:200
	global_load_dword v75, v77, s[52:53] offset:204
	s_ashr_i32 s49, s48, 31
	s_lshl_b64 s[4:5], s[48:49], 18
	s_add_u32 s39, s26, s4
	s_addc_u32 s45, s27, s5
	s_ashr_i32 s51, s50, 31
	s_lshl_b64 s[4:5], s[50:51], 18
	s_add_u32 s49, s0, s4
	s_addc_u32 s51, s1, s5
	s_add_i32 s4, s50, s48
	s_lshl_b32 s48, s4, 7
	v_add_u32_e32 v226, v88, v86
	v_add_u32_e32 v227, v89, v86
	v_add_u32_e32 v91, v88, v90
	v_add_u32_e32 v92, v89, v90
	s_mov_b32 s34, s48
	s_and_b64 vcc, exec, s[46:47]
	s_cbranch_vccnz .Lgx_have
	s_and_b32 s4, s34, 0x3c0
	s_lshl_b32 s6, s4, 1
	s_add_u32 s4, s39, s6
	s_addc_u32 s5, s45, 0
	s_add_u32 s6, s49, s6
	s_addc_u32 s7, s51, 0
	s_add_i32 s34, s34, 64
	s_add_u32 m0, s100, 0x0
	s_nop 0
	global_load_lds_dwordx4 v70, s[4:5]
	s_add_u32 m0, s100, 0x4000
	s_nop 0
	global_load_lds_dwordx4 v70, s[6:7]
	s_add_u32 m0, s100, 0x1000
	s_nop 0
	global_load_lds_dwordx4 v72, s[4:5]
	s_add_u32 m0, s100, 0x5000
	s_nop 0
	global_load_lds_dwordx4 v72, s[6:7]
	s_add_u32 m0, s100, 0x2000
	s_nop 0
	global_load_lds_dwordx4 v74, s[4:5]
	s_add_u32 m0, s100, 0x6000
	s_nop 0
	global_load_lds_dwordx4 v74, s[6:7]
	s_add_u32 m0, s100, 0x3000
	s_nop 0
	global_load_lds_dwordx4 v76, s[4:5]
	s_add_u32 m0, s100, 0x7000
	s_nop 0
	global_load_lds_dwordx4 v76, s[6:7]
	s_and_b32 s4, s34, 0x3c0
	s_lshl_b32 s6, s4, 1
	s_add_u32 s4, s39, s6
	s_addc_u32 s5, s45, 0
	s_add_u32 s6, s49, s6
	s_addc_u32 s7, s51, 0
	s_add_i32 s34, s34, 64
	s_add_u32 m0, s100, 0x8000
	s_nop 0
	global_load_lds_dwordx4 v70, s[4:5]
	s_add_u32 m0, s100, 0xc000
	s_nop 0
	global_load_lds_dwordx4 v70, s[6:7]
	s_add_u32 m0, s100, 0x9000
	s_nop 0
	global_load_lds_dwordx4 v72, s[4:5]
	s_add_u32 m0, s100, 0xd000
	s_nop 0
	global_load_lds_dwordx4 v72, s[6:7]
	s_add_u32 m0, s100, 0xa000
	s_nop 0
	global_load_lds_dwordx4 v74, s[4:5]
	s_add_u32 m0, s100, 0xe000
	s_nop 0
	global_load_lds_dwordx4 v74, s[6:7]
	s_add_u32 m0, s100, 0xb000
	s_nop 0
	global_load_lds_dwordx4 v76, s[4:5]
	s_add_u32 m0, s100, 0xf000
	s_nop 0
	global_load_lds_dwordx4 v76, s[6:7]
	s_waitcnt vmcnt(8)
	s_barrier
	ds_read_b128 v[94:97], v226 offset:0
	ds_read_b128 v[98:101], v226 offset:2048
	ds_read_b128 v[102:105], v226 offset:4096
	ds_read_b128 v[106:109], v226 offset:6144
	ds_read_b128 v[110:113], v227 offset:16384
	ds_read_b128 v[114:117], v227 offset:18432
	ds_read_b128 v[118:121], v227 offset:20480
	ds_read_b128 v[122:125], v227 offset:22528
	ds_read_b128 v[126:129], v91 offset:0
	ds_read_b128 v[130:133], v91 offset:2048
	ds_read_b128 v[134:137], v91 offset:4096
	ds_read_b128 v[138:141], v91 offset:6144
	ds_read_b128 v[142:145], v92 offset:16384
	ds_read_b128 v[152:155], v92 offset:18432
	ds_read_b128 v[156:159], v92 offset:20480
	ds_read_b128 v[178:181], v92 offset:22528
	s_waitcnt lgkmcnt(0)
	s_barrier
	s_and_b32 s4, s34, 0x3c0
	s_lshl_b32 s6, s4, 1
	s_add_u32 s4, s39, s6
	s_addc_u32 s5, s45, 0
	s_add_u32 s6, s49, s6
	s_addc_u32 s7, s51, 0
	s_add_i32 s34, s34, 64
	s_add_u32 m0, s100, 0x0
	s_nop 0
	global_load_lds_dwordx4 v70, s[4:5]
	s_add_u32 m0, s100, 0x4000
	s_nop 0
	global_load_lds_dwordx4 v70, s[6:7]
	s_add_u32 m0, s100, 0x1000
	s_nop 0
	global_load_lds_dwordx4 v72, s[4:5]
	s_add_u32 m0, s100, 0x5000
	s_nop 0
	global_load_lds_dwordx4 v72, s[6:7]
	s_add_u32 m0, s100, 0x2000
	s_nop 0
	global_load_lds_dwordx4 v74, s[4:5]
	s_add_u32 m0, s100, 0x6000
	s_nop 0
	global_load_lds_dwordx4 v74, s[6:7]
	s_add_u32 m0, s100, 0x3000
	s_nop 0
	global_load_lds_dwordx4 v76, s[4:5]
	s_add_u32 m0, s100, 0x7000
	s_nop 0
	global_load_lds_dwordx4 v76, s[6:7]
	s_waitcnt vmcnt(8)
	s_branch .Lgx_k0

; DI float sigm(float x) { return __builtin_amdgcn_rcpf(1.f + __expf(-x)); }
; DI void phase_merge(const Params& p, int l, LAS char* lds) {
;     ...
;         if (gate) {
; #pragma unroll
;             for (int ni = 0; ni < 4; ++ni) {
;                 const f32x4 bv = bvv[ni];
; #pragma unroll
;                 for (int mi = 0; mi < 4; ++mi) {
;                     const f32x4 a = acc[mi][ni] + bv;
;                     const unsigned q0 = (unsigned)(fmaxf(sigm(a[0]) * 255.f, 1.f) + 0.5f), q1 = (unsigned)(fmaxf(sigm(a[1]) * 255.f, 1.f) + 0.5f);
;                     const unsigned q2 = (unsigned)(fmaxf(sigm(a[2]) * 255.f, 1.f) + 0.5f), q3 = (unsigned)(fmaxf(sigm(a[3]) * 255.f, 1.f) + 0.5f);
;                     st[(mi * 4 + ni) * 256] = q0 | (q1 << 8) | (q2 << 16) | (q3 << 24);
;                 }
;             }
.Lgxk15_dn:
	s_setprio 0
	v_add_f32_e32 v186, v66, v62
	v_add_f32_e32 v187, v68, v63
	v_add_f32_e32 v188, v69, v64
	v_add_f32_e32 v189, v93, v65
	v_mul_f32_e32 v186, 0xbfb8aa3b, v186
	v_mul_f32_e32 v187, 0xbfb8aa3b, v187
	v_mul_f32_e32 v188, 0xbfb8aa3b, v188
	v_mul_f32_e32 v189, 0xbfb8aa3b, v189
	v_exp_f32_e32 v186, v186
	v_exp_f32_e32 v187, v187
	v_exp_f32_e32 v188, v188
	v_exp_f32_e32 v189, v189
	v_add_f32_e32 v186, 1.0, v186
	v_add_f32_e32 v187, 1.0, v187
	v_add_f32_e32 v188, 1.0, v188
	v_add_f32_e32 v189, 1.0, v189
	v_rcp_f32_e32 v186, v186
	v_rcp_f32_e32 v187, v187
	v_rcp_f32_e32 v188, v188
	v_rcp_f32_e32 v189, v189
	v_mul_f32_e32 v186, 0x437f0000, v186
	v_mul_f32_e32 v187, 0x437f0000, v187
	v_mul_f32_e32 v188, 0x437f0000, v188
	v_mul_f32_e32 v189, 0x437f0000, v189
	v_max_f32_e32 v186, 1.0, v186
	v_max_f32_e32 v187, 1.0, v187
	v_max_f32_e32 v188, 1.0, v188
	v_max_f32_e32 v189, 1.0, v189
	v_add_f32_e32 v186, 0.5, v186
	v_add_f32_e32 v187, 0.5, v187
	v_add_f32_e32 v188, 0.5, v188
	v_add_f32_e32 v189, 0.5, v189
	v_cvt_u32_f32_e32 v186, v186
	v_cvt_u32_f32_e32 v187, v187
	v_cvt_u32_f32_sdwa v188, v188 dst_sel:WORD_1 dst_unused:UNUSED_PAD src0_sel:DWORD
	v_cvt_u32_f32_sdwa v189, v189 dst_sel:BYTE_3 dst_unused:UNUSED_PAD src0_sel:DWORD
	v_lshl_or_b32 v186, v187, 8, v186
	s_nop 0
	v_or3_b32 v186, v186, v188, v189
	global_store_dword v1, v186, s[40:41] offset:0
	v_add_f32_e32 v190, v146, v58
	v_add_f32_e32 v191, v147, v59
	v_add_f32_e32 v192, v148, v60
	v_add_f32_e32 v193, v160, v61
	v_mul_f32_e32 v190, 0xbfb8aa3b, v190
	v_mul_f32_e32 v191, 0xbfb8aa3b, v191
	v_mul_f32_e32 v192, 0xbfb8aa3b, v192
	v_mul_f32_e32 v193, 0xbfb8aa3b, v193
	v_exp_f32_e32 v190, v190
	v_exp_f32_e32 v191, v191
	v_exp_f32_e32 v192, v192
	v_exp_f32_e32 v193, v193
	v_add_f32_e32 v190, 1.0, v190
	v_add_f32_e32 v191, 1.0, v191
	v_add_f32_e32 v192, 1.0, v192
	v_add_f32_e32 v193, 1.0, v193
	v_rcp_f32_e32 v190, v190
	v_rcp_f32_e32 v191, v191
	v_rcp_f32_e32 v192, v192
	v_rcp_f32_e32 v193, v193
	v_mul_f32_e32 v190, 0x437f0000, v190
	v_mul_f32_e32 v191, 0x437f0000, v191
	v_mul_f32_e32 v192, 0x437f0000, v192
	v_mul_f32_e32 v193, 0x437f0000, v193
	v_max_f32_e32 v190, 1.0, v190
	v_max_f32_e32 v191, 1.0, v191
	v_max_f32_e32 v192, 1.0, v192
	v_max_f32_e32 v193, 1.0, v193
	v_add_f32_e32 v190, 0.5, v190
	v_add_f32_e32 v191, 0.5, v191
	v_add_f32_e32 v192, 0.5, v192
	v_add_f32_e32 v193, 0.5, v193
	v_cvt_u32_f32_e32 v190, v190
	v_cvt_u32_f32_e32 v191, v191
	v_cvt_u32_f32_sdwa v192, v192 dst_sel:WORD_1 dst_unused:UNUSED_PAD src0_sel:DWORD
	v_cvt_u32_f32_sdwa v193, v193 dst_sel:BYTE_3 dst_unused:UNUSED_PAD src0_sel:DWORD
	v_lshl_or_b32 v190, v191, 8, v190
	s_nop 0
	v_or3_b32 v190, v190, v192, v193
	global_store_dword v1, v190, s[40:41] offset:1024
	v_add_f32_e32 v186, v161, v54
	v_add_f32_e32 v187, v182, v55
	v_add_f32_e32 v188, v183, v56
	v_add_f32_e32 v189, v184, v57
	v_mul_f32_e32 v186, 0xbfb8aa3b, v186
	v_mul_f32_e32 v187, 0xbfb8aa3b, v187
	v_mul_f32_e32 v188, 0xbfb8aa3b, v188
	v_mul_f32_e32 v189, 0xbfb8aa3b, v189
	v_exp_f32_e32 v186, v186
	v_exp_f32_e32 v187, v187
	v_exp_f32_e32 v188, v188
	v_exp_f32_e32 v189, v189
	v_add_f32_e32 v186, 1.0, v186
	v_add_f32_e32 v187, 1.0, v187
	v_add_f32_e32 v188, 1.0, v188
	v_add_f32_e32 v189, 1.0, v189
	v_rcp_f32_e32 v186, v186
	v_rcp_f32_e32 v187, v187
	v_rcp_f32_e32 v188, v188
	v_rcp_f32_e32 v189, v189
	v_mul_f32_e32 v186, 0x437f0000, v186
	v_mul_f32_e32 v187, 0x437f0000, v187
	v_mul_f32_e32 v188, 0x437f0000, v188
	v_mul_f32_e32 v189, 0x437f0000, v189
	v_max_f32_e32 v186, 1.0, v186
	v_max_f32_e32 v187, 1.0, v187
	v_max_f32_e32 v188, 1.0, v188
	v_max_f32_e32 v189, 1.0, v189
	v_add_f32_e32 v186, 0.5, v186
	v_add_f32_e32 v187, 0.5, v187
	v_add_f32_e32 v188, 0.5, v188
	v_add_f32_e32 v189, 0.5, v189
	v_cvt_u32_f32_e32 v186, v186
	v_cvt_u32_f32_e32 v187, v187
	v_cvt_u32_f32_sdwa v188, v188 dst_sel:WORD_1 dst_unused:UNUSED_PAD src0_sel:DWORD
	v_cvt_u32_f32_sdwa v189, v189 dst_sel:BYTE_3 dst_unused:UNUSED_PAD src0_sel:DWORD
	v_lshl_or_b32 v186, v187, 8, v186
	s_nop 0
	v_or3_b32 v186, v186, v188, v189
	global_store_dword v1, v186, s[40:41] offset:2048
	v_add_f32_e32 v190, v185, v50
	v_add_f32_e32 v191, v71, v51
	v_add_f32_e32 v192, v73, v52
	v_add_f32_e32 v193, v75, v53
	v_mul_f32_e32 v190, 0xbfb8aa3b, v190
	v_mul_f32_e32 v191, 0xbfb8aa3b, v191
	v_mul_f32_e32 v192, 0xbfb8aa3b, v192
	v_mul_f32_e32 v193, 0xbfb8aa3b, v193
	v_exp_f32_e32 v190, v190
	v_exp_f32_e32 v191, v191
	v_exp_f32_e32 v192, v192
	v_exp_f32_e32 v193, v193
	v_add_f32_e32 v190, 1.0, v190
	v_add_f32_e32 v191, 1.0, v191
	v_add_f32_e32 v192, 1.0, v192
	v_add_f32_e32 v193, 1.0, v193
	v_rcp_f32_e32 v190, v190
	v_rcp_f32_e32 v191, v191
	v_rcp_f32_e32 v192, v192
	v_rcp_f32_e32 v193, v193
	v_mul_f32_e32 v190, 0x437f0000, v190
	v_mul_f32_e32 v191, 0x437f0000, v191
	v_mul_f32_e32 v192, 0x437f0000, v192
	v_mul_f32_e32 v193, 0x437f0000, v193
	v_max_f32_e32 v190, 1.0, v190
	v_max_f32_e32 v191, 1.0, v191
	v_max_f32_e32 v192, 1.0, v192
	v_max_f32_e32 v193, 1.0, v193
	v_add_f32_e32 v190, 0.5, v190
	v_add_f32_e32 v191, 0.5, v191
	v_add_f32_e32 v192, 0.5, v192
	v_add_f32_e32 v193, 0.5, v193
	v_cvt_u32_f32_e32 v190, v190
	v_cvt_u32_f32_e32 v191, v191
	v_cvt_u32_f32_sdwa v192, v192 dst_sel:WORD_1 dst_unused:UNUSED_PAD src0_sel:DWORD
	v_cvt_u32_f32_sdwa v193, v193 dst_sel:BYTE_3 dst_unused:UNUSED_PAD src0_sel:DWORD
	v_lshl_or_b32 v190, v191, 8, v190
	s_nop 0
	v_or3_b32 v190, v190, v192, v193
	global_store_dword v1, v190, s[40:41] offset:3072
	s_add_u32 s40, s40, 0x1000
	s_addc_u32 s41, s41, 0
	v_add_f32_e32 v186, v66, v46
	v_add_f32_e32 v187, v68, v47
	v_add_f32_e32 v188, v69, v48
	v_add_f32_e32 v189, v93, v49
; DI float sigm(float x) { return __builtin_amdgcn_rcpf(1.f + __expf(-x)); }
; DI void phase_merge(const Params& p, int l, LAS char* lds) {
;     ...
;         if (gate) {
; #pragma unroll
;             for (int ni = 0; ni < 4; ++ni) {
;                 const f32x4 bv = bvv[ni];
; #pragma unroll
;                 for (int mi = 0; mi < 4; ++mi) {
;                     const f32x4 a = acc[mi][ni] + bv;
;                     const unsigned q0 = (unsigned)(fmaxf(sigm(a[0]) * 255.f, 1.f) + 0.5f), q1 = (unsigned)(fmaxf(sigm(a[1]) * 255.f, 1.f) + 0.5f);
;                     const unsigned q2 = (unsigned)(fmaxf(sigm(a[2]) * 255.f, 1.f) + 0.5f), q3 = (unsigned)(fmaxf(sigm(a[3]) * 255.f, 1.f) + 0.5f);
;                     st[(mi * 4 + ni) * 256] = q0 | (q1 << 8) | (q2 << 16) | (q3 << 24);
;                 }
;             }
	v_mul_f32_e32 v186, 0xbfb8aa3b, v186
	v_mul_f32_e32 v187, 0xbfb8aa3b, v187
	v_mul_f32_e32 v188, 0xbfb8aa3b, v188
	v_mul_f32_e32 v189, 0xbfb8aa3b, v189
	v_exp_f32_e32 v186, v186
	v_exp_f32_e32 v187, v187
	v_exp_f32_e32 v188, v188
	v_exp_f32_e32 v189, v189
	v_add_f32_e32 v186, 1.0, v186
	v_add_f32_e32 v187, 1.0, v187
	v_add_f32_e32 v188, 1.0, v188
	v_add_f32_e32 v189, 1.0, v189
	v_rcp_f32_e32 v186, v186
	v_rcp_f32_e32 v187, v187
	v_rcp_f32_e32 v188, v188
	v_rcp_f32_e32 v189, v189
	v_mul_f32_e32 v186, 0x437f0000, v186
	v_mul_f32_e32 v187, 0x437f0000, v187
	v_mul_f32_e32 v188, 0x437f0000, v188
	v_mul_f32_e32 v189, 0x437f0000, v189
	v_max_f32_e32 v186, 1.0, v186
	v_max_f32_e32 v187, 1.0, v187
	v_max_f32_e32 v188, 1.0, v188
	v_max_f32_e32 v189, 1.0, v189
	v_add_f32_e32 v186, 0.5, v186
	v_add_f32_e32 v187, 0.5, v187
	v_add_f32_e32 v188, 0.5, v188
	v_add_f32_e32 v189, 0.5, v189
	v_cvt_u32_f32_e32 v186, v186
	v_cvt_u32_f32_e32 v187, v187
	v_cvt_u32_f32_sdwa v188, v188 dst_sel:WORD_1 dst_unused:UNUSED_PAD src0_sel:DWORD
	v_cvt_u32_f32_sdwa v189, v189 dst_sel:BYTE_3 dst_unused:UNUSED_PAD src0_sel:DWORD
	v_lshl_or_b32 v186, v187, 8, v186
	s_nop 0
	v_or3_b32 v186, v186, v188, v189
	global_store_dword v1, v186, s[40:41] offset:0
	v_add_f32_e32 v190, v146, v42
	v_add_f32_e32 v191, v147, v43
	v_add_f32_e32 v192, v148, v44
	v_add_f32_e32 v193, v160, v45
	v_mul_f32_e32 v190, 0xbfb8aa3b, v190
	v_mul_f32_e32 v191, 0xbfb8aa3b, v191
	v_mul_f32_e32 v192, 0xbfb8aa3b, v192
	v_mul_f32_e32 v193, 0xbfb8aa3b, v193
	v_exp_f32_e32 v190, v190
	v_exp_f32_e32 v191, v191
	v_exp_f32_e32 v192, v192
	v_exp_f32_e32 v193, v193
	v_add_f32_e32 v190, 1.0, v190
	v_add_f32_e32 v191, 1.0, v191
	v_add_f32_e32 v192, 1.0, v192
	v_add_f32_e32 v193, 1.0, v193
	v_rcp_f32_e32 v190, v190
	v_rcp_f32_e32 v191, v191
	v_rcp_f32_e32 v192, v192
	v_rcp_f32_e32 v193, v193
	v_mul_f32_e32 v190, 0x437f0000, v190
	v_mul_f32_e32 v191, 0x437f0000, v191
	v_mul_f32_e32 v192, 0x437f0000, v192
	v_mul_f32_e32 v193, 0x437f0000, v193
	v_max_f32_e32 v190, 1.0, v190
	v_max_f32_e32 v191, 1.0, v191
	v_max_f32_e32 v192, 1.0, v192
	v_max_f32_e32 v193, 1.0, v193
	v_add_f32_e32 v190, 0.5, v190
	v_add_f32_e32 v191, 0.5, v191
	v_add_f32_e32 v192, 0.5, v192
	v_add_f32_e32 v193, 0.5, v193
	v_cvt_u32_f32_e32 v190, v190
	v_cvt_u32_f32_e32 v191, v191
	v_cvt_u32_f32_sdwa v192, v192 dst_sel:WORD_1 dst_unused:UNUSED_PAD src0_sel:DWORD
	v_cvt_u32_f32_sdwa v193, v193 dst_sel:BYTE_3 dst_unused:UNUSED_PAD src0_sel:DWORD
	v_lshl_or_b32 v190, v191, 8, v190
	s_nop 0
	v_or3_b32 v190, v190, v192, v193
	global_store_dword v1, v190, s[40:41] offset:1024
	v_add_f32_e32 v186, v161, v38
	v_add_f32_e32 v187, v182, v39
	v_add_f32_e32 v188, v183, v40
	v_add_f32_e32 v189, v184, v41
	v_mul_f32_e32 v186, 0xbfb8aa3b, v186
	v_mul_f32_e32 v187, 0xbfb8aa3b, v187
	v_mul_f32_e32 v188, 0xbfb8aa3b, v188
	v_mul_f32_e32 v189, 0xbfb8aa3b, v189
	v_exp_f32_e32 v186, v186
	v_exp_f32_e32 v187, v187
	v_exp_f32_e32 v188, v188
	v_exp_f32_e32 v189, v189
	v_add_f32_e32 v186, 1.0, v186
	v_add_f32_e32 v187, 1.0, v187
	v_add_f32_e32 v188, 1.0, v188
	v_add_f32_e32 v189, 1.0, v189
	v_rcp_f32_e32 v186, v186
	v_rcp_f32_e32 v187, v187
	v_rcp_f32_e32 v188, v188
	v_rcp_f32_e32 v189, v189
	v_mul_f32_e32 v186, 0x437f0000, v186
	v_mul_f32_e32 v187, 0x437f0000, v187
	v_mul_f32_e32 v188, 0x437f0000, v188
	v_mul_f32_e32 v189, 0x437f0000, v189
	v_max_f32_e32 v186, 1.0, v186
	v_max_f32_e32 v187, 1.0, v187
	v_max_f32_e32 v188, 1.0, v188
	v_max_f32_e32 v189, 1.0, v189
	v_add_f32_e32 v186, 0.5, v186
	v_add_f32_e32 v187, 0.5, v187
	v_add_f32_e32 v188, 0.5, v188
	v_add_f32_e32 v189, 0.5, v189
	v_cvt_u32_f32_e32 v186, v186
	v_cvt_u32_f32_e32 v187, v187
	v_cvt_u32_f32_sdwa v188, v188 dst_sel:WORD_1 dst_unused:UNUSED_PAD src0_sel:DWORD
	v_cvt_u32_f32_sdwa v189, v189 dst_sel:BYTE_3 dst_unused:UNUSED_PAD src0_sel:DWORD
	v_lshl_or_b32 v186, v187, 8, v186
	s_nop 0
	v_or3_b32 v186, v186, v188, v189
	global_store_dword v1, v186, s[40:41] offset:2048
	v_add_f32_e32 v190, v185, v34
	v_add_f32_e32 v191, v71, v35
	v_add_f32_e32 v192, v73, v36
	v_add_f32_e32 v193, v75, v37
	v_mul_f32_e32 v190, 0xbfb8aa3b, v190
	v_mul_f32_e32 v191, 0xbfb8aa3b, v191
	v_mul_f32_e32 v192, 0xbfb8aa3b, v192
	v_mul_f32_e32 v193, 0xbfb8aa3b, v193
	v_exp_f32_e32 v190, v190
	v_exp_f32_e32 v191, v191
	v_exp_f32_e32 v192, v192
	v_exp_f32_e32 v193, v193
	v_add_f32_e32 v190, 1.0, v190
	v_add_f32_e32 v191, 1.0, v191
	v_add_f32_e32 v192, 1.0, v192
	v_add_f32_e32 v193, 1.0, v193
	v_rcp_f32_e32 v190, v190
	v_rcp_f32_e32 v191, v191
	v_rcp_f32_e32 v192, v192
	v_rcp_f32_e32 v193, v193
	v_mul_f32_e32 v190, 0x437f0000, v190
	v_mul_f32_e32 v191, 0x437f0000, v191
	v_mul_f32_e32 v192, 0x437f0000, v192
	v_mul_f32_e32 v193, 0x437f0000, v193
	v_max_f32_e32 v190, 1.0, v190
	v_max_f32_e32 v191, 1.0, v191
	v_max_f32_e32 v192, 1.0, v192
	v_max_f32_e32 v193, 1.0, v193
	v_add_f32_e32 v190, 0.5, v190
	v_add_f32_e32 v191, 0.5, v191
	v_add_f32_e32 v192, 0.5, v192
	v_add_f32_e32 v193, 0.5, v193
	v_cvt_u32_f32_e32 v190, v190
	v_cvt_u32_f32_e32 v191, v191
	v_cvt_u32_f32_sdwa v192, v192 dst_sel:WORD_1 dst_unused:UNUSED_PAD src0_sel:DWORD
	v_cvt_u32_f32_sdwa v193, v193 dst_sel:BYTE_3 dst_unused:UNUSED_PAD src0_sel:DWORD
	v_lshl_or_b32 v190, v191, 8, v190
	s_nop 0
	v_or3_b32 v190, v190, v192, v193
	global_store_dword v1, v190, s[40:41] offset:3072
	s_add_u32 s40, s40, 0x1000
	s_addc_u32 s41, s41, 0
	v_add_f32_e32 v186, v66, v30
	v_add_f32_e32 v187, v68, v31
	v_add_f32_e32 v188, v69, v32
	v_add_f32_e32 v189, v93, v33
	v_mul_f32_e32 v186, 0xbfb8aa3b, v186
	v_mul_f32_e32 v187, 0xbfb8aa3b, v187
	v_mul_f32_e32 v188, 0xbfb8aa3b, v188
	v_mul_f32_e32 v189, 0xbfb8aa3b, v189
; DI float sigm(float x) { return __builtin_amdgcn_rcpf(1.f + __expf(-x)); }
; DI void phase_merge(const Params& p, int l, LAS char* lds) {
;     ...
;         if (gate) {
; #pragma unroll
;             for (int ni = 0; ni < 4; ++ni) {
;                 const f32x4 bv = bvv[ni];
; #pragma unroll
;                 for (int mi = 0; mi < 4; ++mi) {
;                     const f32x4 a = acc[mi][ni] + bv;
;                     const unsigned q0 = (unsigned)(fmaxf(sigm(a[0]) * 255.f, 1.f) + 0.5f), q1 = (unsigned)(fmaxf(sigm(a[1]) * 255.f, 1.f) + 0.5f);
;                     const unsigned q2 = (unsigned)(fmaxf(sigm(a[2]) * 255.f, 1.f) + 0.5f), q3 = (unsigned)(fmaxf(sigm(a[3]) * 255.f, 1.f) + 0.5f);
;                     st[(mi * 4 + ni) * 256] = q0 | (q1 << 8) | (q2 << 16) | (q3 << 24);
;                 }
;             }
	v_exp_f32_e32 v186, v186
	v_exp_f32_e32 v187, v187
	v_exp_f32_e32 v188, v188
	v_exp_f32_e32 v189, v189
	v_add_f32_e32 v186, 1.0, v186
	v_add_f32_e32 v187, 1.0, v187
	v_add_f32_e32 v188, 1.0, v188
	v_add_f32_e32 v189, 1.0, v189
	v_rcp_f32_e32 v186, v186
	v_rcp_f32_e32 v187, v187
	v_rcp_f32_e32 v188, v188
	v_rcp_f32_e32 v189, v189
	v_mul_f32_e32 v186, 0x437f0000, v186
	v_mul_f32_e32 v187, 0x437f0000, v187
	v_mul_f32_e32 v188, 0x437f0000, v188
	v_mul_f32_e32 v189, 0x437f0000, v189
	v_max_f32_e32 v186, 1.0, v186
	v_max_f32_e32 v187, 1.0, v187
	v_max_f32_e32 v188, 1.0, v188
	v_max_f32_e32 v189, 1.0, v189
	v_add_f32_e32 v186, 0.5, v186
	v_add_f32_e32 v187, 0.5, v187
	v_add_f32_e32 v188, 0.5, v188
	v_add_f32_e32 v189, 0.5, v189
	v_cvt_u32_f32_e32 v186, v186
	v_cvt_u32_f32_e32 v187, v187
	v_cvt_u32_f32_sdwa v188, v188 dst_sel:WORD_1 dst_unused:UNUSED_PAD src0_sel:DWORD
	v_cvt_u32_f32_sdwa v189, v189 dst_sel:BYTE_3 dst_unused:UNUSED_PAD src0_sel:DWORD
	v_lshl_or_b32 v186, v187, 8, v186
	s_nop 0
	v_or3_b32 v186, v186, v188, v189
	global_store_dword v1, v186, s[40:41] offset:0
	v_add_f32_e32 v190, v146, v26
	v_add_f32_e32 v191, v147, v27
	v_add_f32_e32 v192, v148, v28
	v_add_f32_e32 v193, v160, v29
	v_mul_f32_e32 v190, 0xbfb8aa3b, v190
	v_mul_f32_e32 v191, 0xbfb8aa3b, v191
	v_mul_f32_e32 v192, 0xbfb8aa3b, v192
	v_mul_f32_e32 v193, 0xbfb8aa3b, v193
	v_exp_f32_e32 v190, v190
	v_exp_f32_e32 v191, v191
	v_exp_f32_e32 v192, v192
	v_exp_f32_e32 v193, v193
	v_add_f32_e32 v190, 1.0, v190
	v_add_f32_e32 v191, 1.0, v191
	v_add_f32_e32 v192, 1.0, v192
	v_add_f32_e32 v193, 1.0, v193
	v_rcp_f32_e32 v190, v190
	v_rcp_f32_e32 v191, v191
	v_rcp_f32_e32 v192, v192
	v_rcp_f32_e32 v193, v193
	v_mul_f32_e32 v190, 0x437f0000, v190
	v_mul_f32_e32 v191, 0x437f0000, v191
	v_mul_f32_e32 v192, 0x437f0000, v192
	v_mul_f32_e32 v193, 0x437f0000, v193
	v_max_f32_e32 v190, 1.0, v190
	v_max_f32_e32 v191, 1.0, v191
	v_max_f32_e32 v192, 1.0, v192
	v_max_f32_e32 v193, 1.0, v193
	v_add_f32_e32 v190, 0.5, v190
	v_add_f32_e32 v191, 0.5, v191
	v_add_f32_e32 v192, 0.5, v192
	v_add_f32_e32 v193, 0.5, v193
	v_cvt_u32_f32_e32 v190, v190
	v_cvt_u32_f32_e32 v191, v191
	v_cvt_u32_f32_sdwa v192, v192 dst_sel:WORD_1 dst_unused:UNUSED_PAD src0_sel:DWORD
	v_cvt_u32_f32_sdwa v193, v193 dst_sel:BYTE_3 dst_unused:UNUSED_PAD src0_sel:DWORD
	v_lshl_or_b32 v190, v191, 8, v190
	s_nop 0
	v_or3_b32 v190, v190, v192, v193
	global_store_dword v1, v190, s[40:41] offset:1024
	v_add_f32_e32 v186, v161, v22
	v_add_f32_e32 v187, v182, v23
	v_add_f32_e32 v188, v183, v24
	v_add_f32_e32 v189, v184, v25
	v_mul_f32_e32 v186, 0xbfb8aa3b, v186
	v_mul_f32_e32 v187, 0xbfb8aa3b, v187
	v_mul_f32_e32 v188, 0xbfb8aa3b, v188
	v_mul_f32_e32 v189, 0xbfb8aa3b, v189
	v_exp_f32_e32 v186, v186
	v_exp_f32_e32 v187, v187
	v_exp_f32_e32 v188, v188
	v_exp_f32_e32 v189, v189
	v_add_f32_e32 v186, 1.0, v186
	v_add_f32_e32 v187, 1.0, v187
	v_add_f32_e32 v188, 1.0, v188
	v_add_f32_e32 v189, 1.0, v189
	v_rcp_f32_e32 v186, v186
	v_rcp_f32_e32 v187, v187
	v_rcp_f32_e32 v188, v188
	v_rcp_f32_e32 v189, v189
	v_mul_f32_e32 v186, 0x437f0000, v186
	v_mul_f32_e32 v187, 0x437f0000, v187
	v_mul_f32_e32 v188, 0x437f0000, v188
	v_mul_f32_e32 v189, 0x437f0000, v189
	v_max_f32_e32 v186, 1.0, v186
	v_max_f32_e32 v187, 1.0, v187
	v_max_f32_e32 v188, 1.0, v188
	v_max_f32_e32 v189, 1.0, v189
	v_add_f32_e32 v186, 0.5, v186
	v_add_f32_e32 v187, 0.5, v187
	v_add_f32_e32 v188, 0.5, v188
	v_add_f32_e32 v189, 0.5, v189
	v_cvt_u32_f32_e32 v186, v186
	v_cvt_u32_f32_e32 v187, v187
	v_cvt_u32_f32_sdwa v188, v188 dst_sel:WORD_1 dst_unused:UNUSED_PAD src0_sel:DWORD
	v_cvt_u32_f32_sdwa v189, v189 dst_sel:BYTE_3 dst_unused:UNUSED_PAD src0_sel:DWORD
	v_lshl_or_b32 v186, v187, 8, v186
	s_nop 0
	v_or3_b32 v186, v186, v188, v189
	global_store_dword v1, v186, s[40:41] offset:2048
	v_add_f32_e32 v190, v185, v18
	v_add_f32_e32 v191, v71, v19
	v_add_f32_e32 v192, v73, v20
	v_add_f32_e32 v193, v75, v21
	v_mul_f32_e32 v190, 0xbfb8aa3b, v190
	v_mul_f32_e32 v191, 0xbfb8aa3b, v191
	v_mul_f32_e32 v192, 0xbfb8aa3b, v192
	v_mul_f32_e32 v193, 0xbfb8aa3b, v193
	v_exp_f32_e32 v190, v190
	v_exp_f32_e32 v191, v191
	v_exp_f32_e32 v192, v192
	v_exp_f32_e32 v193, v193
	v_add_f32_e32 v190, 1.0, v190
	v_add_f32_e32 v191, 1.0, v191
	v_add_f32_e32 v192, 1.0, v192
	v_add_f32_e32 v193, 1.0, v193
	v_rcp_f32_e32 v190, v190
	v_rcp_f32_e32 v191, v191
	v_rcp_f32_e32 v192, v192
	v_rcp_f32_e32 v193, v193
	v_mul_f32_e32 v190, 0x437f0000, v190
	v_mul_f32_e32 v191, 0x437f0000, v191
	v_mul_f32_e32 v192, 0x437f0000, v192
	v_mul_f32_e32 v193, 0x437f0000, v193
	v_max_f32_e32 v190, 1.0, v190
	v_max_f32_e32 v191, 1.0, v191
	v_max_f32_e32 v192, 1.0, v192
	v_max_f32_e32 v193, 1.0, v193
	v_add_f32_e32 v190, 0.5, v190
	v_add_f32_e32 v191, 0.5, v191
	v_add_f32_e32 v192, 0.5, v192
	v_add_f32_e32 v193, 0.5, v193
	v_cvt_u32_f32_e32 v190, v190
	v_cvt_u32_f32_e32 v191, v191
	v_cvt_u32_f32_sdwa v192, v192 dst_sel:WORD_1 dst_unused:UNUSED_PAD src0_sel:DWORD
	v_cvt_u32_f32_sdwa v193, v193 dst_sel:BYTE_3 dst_unused:UNUSED_PAD src0_sel:DWORD
	v_lshl_or_b32 v190, v191, 8, v190
	s_nop 0
	v_or3_b32 v190, v190, v192, v193
	global_store_dword v1, v190, s[40:41] offset:3072
	s_add_u32 s40, s40, 0x1000
	s_addc_u32 s41, s41, 0
	v_add_f32_e32 v186, v66, v14
	v_add_f32_e32 v187, v68, v15
	v_add_f32_e32 v188, v69, v16
	v_add_f32_e32 v189, v93, v17
; DI float sigm(float x) { return __builtin_amdgcn_rcpf(1.f + __expf(-x)); }
; DI void phase_merge(const Params& p, int l, LAS char* lds) {
;     ...
;         if (gate) {
; #pragma unroll
;             for (int ni = 0; ni < 4; ++ni) {
;                 const f32x4 bv = bvv[ni];
; #pragma unroll
;                 for (int mi = 0; mi < 4; ++mi) {
;                     const f32x4 a = acc[mi][ni] + bv;
;                     const unsigned q0 = (unsigned)(fmaxf(sigm(a[0]) * 255.f, 1.f) + 0.5f), q1 = (unsigned)(fmaxf(sigm(a[1]) * 255.f, 1.f) + 0.5f);
;                     const unsigned q2 = (unsigned)(fmaxf(sigm(a[2]) * 255.f, 1.f) + 0.5f), q3 = (unsigned)(fmaxf(sigm(a[3]) * 255.f, 1.f) + 0.5f);
;                     st[(mi * 4 + ni) * 256] = q0 | (q1 << 8) | (q2 << 16) | (q3 << 24);
;                 }
;             }
	v_mul_f32_e32 v186, 0xbfb8aa3b, v186
	v_mul_f32_e32 v187, 0xbfb8aa3b, v187
	v_mul_f32_e32 v188, 0xbfb8aa3b, v188
	v_mul_f32_e32 v189, 0xbfb8aa3b, v189
	v_exp_f32_e32 v186, v186
	v_exp_f32_e32 v187, v187
	v_exp_f32_e32 v188, v188
	v_exp_f32_e32 v189, v189
	v_add_f32_e32 v186, 1.0, v186
	v_add_f32_e32 v187, 1.0, v187
	v_add_f32_e32 v188, 1.0, v188
	v_add_f32_e32 v189, 1.0, v189
	v_rcp_f32_e32 v186, v186
	v_rcp_f32_e32 v187, v187
	v_rcp_f32_e32 v188, v188
	v_rcp_f32_e32 v189, v189
	v_mul_f32_e32 v186, 0x437f0000, v186
	v_mul_f32_e32 v187, 0x437f0000, v187
	v_mul_f32_e32 v188, 0x437f0000, v188
	v_mul_f32_e32 v189, 0x437f0000, v189
	v_max_f32_e32 v186, 1.0, v186
	v_max_f32_e32 v187, 1.0, v187
	v_max_f32_e32 v188, 1.0, v188
	v_max_f32_e32 v189, 1.0, v189
	v_add_f32_e32 v186, 0.5, v186
	v_add_f32_e32 v187, 0.5, v187
	v_add_f32_e32 v188, 0.5, v188
	v_add_f32_e32 v189, 0.5, v189
	v_cvt_u32_f32_e32 v186, v186
	v_cvt_u32_f32_e32 v187, v187
	v_cvt_u32_f32_sdwa v188, v188 dst_sel:WORD_1 dst_unused:UNUSED_PAD src0_sel:DWORD
	v_cvt_u32_f32_sdwa v189, v189 dst_sel:BYTE_3 dst_unused:UNUSED_PAD src0_sel:DWORD
	v_lshl_or_b32 v186, v187, 8, v186
	s_nop 0
	v_or3_b32 v186, v186, v188, v189
	global_store_dword v1, v186, s[40:41] offset:0
	v_add_f32_e32 v190, v146, v10
	v_add_f32_e32 v191, v147, v11
	v_add_f32_e32 v192, v148, v12
	v_add_f32_e32 v193, v160, v13
	v_mul_f32_e32 v190, 0xbfb8aa3b, v190
	v_mul_f32_e32 v191, 0xbfb8aa3b, v191
	v_mul_f32_e32 v192, 0xbfb8aa3b, v192
	v_mul_f32_e32 v193, 0xbfb8aa3b, v193
	v_exp_f32_e32 v190, v190
	v_exp_f32_e32 v191, v191
	v_exp_f32_e32 v192, v192
	v_exp_f32_e32 v193, v193
	v_add_f32_e32 v190, 1.0, v190
	v_add_f32_e32 v191, 1.0, v191
	v_add_f32_e32 v192, 1.0, v192
	v_add_f32_e32 v193, 1.0, v193
	v_rcp_f32_e32 v190, v190
	v_rcp_f32_e32 v191, v191
	v_rcp_f32_e32 v192, v192
	v_rcp_f32_e32 v193, v193
	v_mul_f32_e32 v190, 0x437f0000, v190
	v_mul_f32_e32 v191, 0x437f0000, v191
	v_mul_f32_e32 v192, 0x437f0000, v192
	v_mul_f32_e32 v193, 0x437f0000, v193
	v_max_f32_e32 v190, 1.0, v190
	v_max_f32_e32 v191, 1.0, v191
	v_max_f32_e32 v192, 1.0, v192
	v_max_f32_e32 v193, 1.0, v193
	v_add_f32_e32 v190, 0.5, v190
	v_add_f32_e32 v191, 0.5, v191
	v_add_f32_e32 v192, 0.5, v192
	v_add_f32_e32 v193, 0.5, v193
	v_cvt_u32_f32_e32 v190, v190
	v_cvt_u32_f32_e32 v191, v191
	v_cvt_u32_f32_sdwa v192, v192 dst_sel:WORD_1 dst_unused:UNUSED_PAD src0_sel:DWORD
	v_cvt_u32_f32_sdwa v193, v193 dst_sel:BYTE_3 dst_unused:UNUSED_PAD src0_sel:DWORD
	v_lshl_or_b32 v190, v191, 8, v190
	s_nop 0
	v_or3_b32 v190, v190, v192, v193
	global_store_dword v1, v190, s[40:41] offset:1024
	v_add_f32_e32 v186, v161, v6
	v_add_f32_e32 v187, v182, v7
	v_add_f32_e32 v188, v183, v8
	v_add_f32_e32 v189, v184, v9
	v_mul_f32_e32 v186, 0xbfb8aa3b, v186
	v_mul_f32_e32 v187, 0xbfb8aa3b, v187
	v_mul_f32_e32 v188, 0xbfb8aa3b, v188
	v_mul_f32_e32 v189, 0xbfb8aa3b, v189
	v_exp_f32_e32 v186, v186
	v_exp_f32_e32 v187, v187
	v_exp_f32_e32 v188, v188
	v_exp_f32_e32 v189, v189
	v_add_f32_e32 v186, 1.0, v186
	v_add_f32_e32 v187, 1.0, v187
	v_add_f32_e32 v188, 1.0, v188
	v_add_f32_e32 v189, 1.0, v189
	v_rcp_f32_e32 v186, v186
	v_rcp_f32_e32 v187, v187
	v_rcp_f32_e32 v188, v188
	v_rcp_f32_e32 v189, v189
	v_mul_f32_e32 v186, 0x437f0000, v186
	v_mul_f32_e32 v187, 0x437f0000, v187
	v_mul_f32_e32 v188, 0x437f0000, v188
	v_mul_f32_e32 v189, 0x437f0000, v189
	v_max_f32_e32 v186, 1.0, v186
	v_max_f32_e32 v187, 1.0, v187
	v_max_f32_e32 v188, 1.0, v188
	v_max_f32_e32 v189, 1.0, v189
	v_add_f32_e32 v186, 0.5, v186
	v_add_f32_e32 v187, 0.5, v187
	v_add_f32_e32 v188, 0.5, v188
	v_add_f32_e32 v189, 0.5, v189
	v_cvt_u32_f32_e32 v186, v186
	v_cvt_u32_f32_e32 v187, v187
	v_cvt_u32_f32_sdwa v188, v188 dst_sel:WORD_1 dst_unused:UNUSED_PAD src0_sel:DWORD
	v_cvt_u32_f32_sdwa v189, v189 dst_sel:BYTE_3 dst_unused:UNUSED_PAD src0_sel:DWORD
	v_lshl_or_b32 v186, v187, 8, v186
	s_nop 0
	v_or3_b32 v186, v186, v188, v189
	global_store_dword v1, v186, s[40:41] offset:2048
	v_add_f32_e32 v190, v185, v2
	v_add_f32_e32 v191, v71, v3
	v_add_f32_e32 v192, v73, v4
	v_add_f32_e32 v193, v75, v5
	v_mul_f32_e32 v190, 0xbfb8aa3b, v190
	v_mul_f32_e32 v191, 0xbfb8aa3b, v191
	v_mul_f32_e32 v192, 0xbfb8aa3b, v192
	v_mul_f32_e32 v193, 0xbfb8aa3b, v193
	v_exp_f32_e32 v190, v190
	v_exp_f32_e32 v191, v191
	v_exp_f32_e32 v192, v192
	v_exp_f32_e32 v193, v193
	v_add_f32_e32 v190, 1.0, v190
	v_add_f32_e32 v191, 1.0, v191
	v_add_f32_e32 v192, 1.0, v192
	v_add_f32_e32 v193, 1.0, v193
	v_rcp_f32_e32 v190, v190
	v_rcp_f32_e32 v191, v191
	v_rcp_f32_e32 v192, v192
	v_rcp_f32_e32 v193, v193
	v_mul_f32_e32 v190, 0x437f0000, v190
	v_mul_f32_e32 v191, 0x437f0000, v191
	v_mul_f32_e32 v192, 0x437f0000, v192
	v_mul_f32_e32 v193, 0x437f0000, v193
	v_max_f32_e32 v190, 1.0, v190
	v_max_f32_e32 v191, 1.0, v191
	v_max_f32_e32 v192, 1.0, v192
	v_max_f32_e32 v193, 1.0, v193
	v_add_f32_e32 v190, 0.5, v190
	v_add_f32_e32 v191, 0.5, v191
	v_add_f32_e32 v192, 0.5, v192
	v_add_f32_e32 v193, 0.5, v193
	v_cvt_u32_f32_e32 v190, v190
	v_cvt_u32_f32_e32 v191, v191
	v_cvt_u32_f32_sdwa v192, v192 dst_sel:WORD_1 dst_unused:UNUSED_PAD src0_sel:DWORD
	v_cvt_u32_f32_sdwa v193, v193 dst_sel:BYTE_3 dst_unused:UNUSED_PAD src0_sel:DWORD
	v_lshl_or_b32 v190, v191, 8, v190
	s_nop 0
	v_or3_b32 v190, v190, v192, v193
	global_store_dword v1, v190, s[40:41] offset:3072
	s_mov_b64 s[46:47], -1
